# phase 4 (LoRA inputs + shift states) rewritten: all loads of a thread's items issued first, tanh/sigmoid via exp2+rcp
# speedup vs baseline: 1.1511x; 1.0051x over previous
.LBB0_608:
	s_cmp_lt_i32 s68, 5
	s_cselect_b64 s[2:3], -1, 0
	s_cmp_gt_i32 s69, 4
	s_cselect_b64 s[4:5], -1, 0
	s_and_b64 s[2:3], s[2:3], s[4:5]
	s_andn2_b64 vcc, exec, s[2:3]
	s_cbranch_vccnz .LBB0_770
	s_cmp_lg_u32 s88, 0x100
	s_cbranch_scc1 .Llin_orig
	v_readlane_b32 s2, v254, 1
	v_readlane_b32 s3, v254, 2
	s_add_u32 s12, s34, 0xd322200
	s_addc_u32 s13, s35, 0
	s_add_u32 s18, s34, 0x8af2200
	s_addc_u32 s19, s35, 0
	s_sub_u32 s2, s2, 0x138
	s_subb_u32 s3, s3, 0
	s_load_dwordx2 s[20:21], s[2:3], 0x58
	s_load_dwordx2 s[22:23], s[2:3], 0x28
	s_movk_i32 s33, 0x2080
	v_mov_b32_e32 v1, 8
	v_lshl_or_b32 v36, s28, 9, v34
	v_mov_b32_e32 v37, 0xaaaaaaab
	v_mov_b32_e32 v2, v36
	v_mul_hi_u32 v3, v2, v37
	v_lshrrev_b32_e32 v40, 5, v3
	v_mul_u32_u24_e32 v3, 48, v40
	v_sub_u32_e32 v44, v2, v3
	v_mul_u32_u24_e32 v52, 0x300, v40
	v_lshl_add_u32 v52, v44, 4, v52
	v_min_u32_e32 v4, 35, v44
	v_min_u32_e32 v5, 0x207f, v40
	v_mov_b32_e32 v6, 0x5c00
	v_mul_lo_u32 v48, v5, v6
	v_lshl_add_u32 v48, v4, 4, v48
	v_add_u32_e32 v48, 0x1800, v48
	v_lshlrev_b32_e32 v24, 5, v4
	v_add_u32_e32 v24, 0x3000, v24
	v_cmp_gt_u32_e32 vcc, 8, v44
	v_mov_b32_e32 v7, 0xbfb8aa3b
	v_mov_b32_e32 v8, 0xc038aa3b
	v_cndmask_b32_e32 v124, v7, v8, vcc
	v_mov_b32_e32 v7, 1.0
	v_cndmask_b32_e64 v128, v7, 2.0, vcc
	v_cndmask_b32_e64 v132, 0, -1.0, vcc
	v_add_u32_e32 v2, 0x20000, v36
	v_mul_hi_u32 v3, v2, v37
	v_lshrrev_b32_e32 v41, 5, v3
	v_mul_u32_u24_e32 v3, 48, v41
	v_sub_u32_e32 v45, v2, v3
	v_mul_u32_u24_e32 v53, 0x300, v41
	v_lshl_add_u32 v53, v45, 4, v53
	v_min_u32_e32 v4, 35, v45
	v_min_u32_e32 v5, 0x207f, v41
	v_mov_b32_e32 v6, 0x5c00
	v_mul_lo_u32 v49, v5, v6
	v_lshl_add_u32 v49, v4, 4, v49
	v_add_u32_e32 v49, 0x1800, v49
	v_lshlrev_b32_e32 v25, 5, v4
	v_add_u32_e32 v25, 0x3000, v25
	v_cmp_gt_u32_e32 vcc, 8, v45
	v_mov_b32_e32 v7, 0xbfb8aa3b
	v_mov_b32_e32 v8, 0xc038aa3b
	v_cndmask_b32_e32 v125, v7, v8, vcc
	v_mov_b32_e32 v7, 1.0
	v_cndmask_b32_e64 v129, v7, 2.0, vcc
	v_cndmask_b32_e64 v133, 0, -1.0, vcc
	v_add_u32_e32 v2, 0x40000, v36
	v_mul_hi_u32 v3, v2, v37
	v_lshrrev_b32_e32 v42, 5, v3
	v_mul_u32_u24_e32 v3, 48, v42
	v_sub_u32_e32 v46, v2, v3
	v_mul_u32_u24_e32 v54, 0x300, v42
	v_lshl_add_u32 v54, v46, 4, v54
	v_min_u32_e32 v4, 35, v46
	v_min_u32_e32 v5, 0x207f, v42
	v_mov_b32_e32 v6, 0x5c00
	v_mul_lo_u32 v50, v5, v6
	v_lshl_add_u32 v50, v4, 4, v50
	v_add_u32_e32 v50, 0x1800, v50
	v_lshlrev_b32_e32 v26, 5, v4
	v_add_u32_e32 v26, 0x3000, v26
	v_cmp_gt_u32_e32 vcc, 8, v46
	v_mov_b32_e32 v7, 0xbfb8aa3b
	v_mov_b32_e32 v8, 0xc038aa3b
	v_cndmask_b32_e32 v126, v7, v8, vcc
	v_mov_b32_e32 v7, 1.0
	v_cndmask_b32_e64 v130, v7, 2.0, vcc
	v_cndmask_b32_e64 v134, 0, -1.0, vcc
	v_add_u32_e32 v2, 0x60000, v36
	v_mul_hi_u32 v3, v2, v37
	v_lshrrev_b32_e32 v43, 5, v3
	v_mul_u32_u24_e32 v3, 48, v43
	v_sub_u32_e32 v47, v2, v3
	v_mul_u32_u24_e32 v55, 0x300, v43
	v_lshl_add_u32 v55, v47, 4, v55
	v_min_u32_e32 v4, 35, v47
	v_min_u32_e32 v5, 0x207f, v43
	v_mov_b32_e32 v6, 0x5c00
	v_mul_lo_u32 v51, v5, v6
	v_lshl_add_u32 v51, v4, 4, v51
	v_add_u32_e32 v51, 0x1800, v51
	v_lshlrev_b32_e32 v27, 5, v4
	v_add_u32_e32 v27, 0x3000, v27
	v_cmp_gt_u32_e32 vcc, 8, v47
	v_mov_b32_e32 v7, 0xbfb8aa3b
	v_mov_b32_e32 v8, 0xc038aa3b
	v_cndmask_b32_e32 v127, v7, v8, vcc
	v_mov_b32_e32 v7, 1.0
	v_cndmask_b32_e64 v131, v7, 2.0, vcc
	v_cndmask_b32_e64 v135, 0, -1.0, vcc
	s_waitcnt lgkmcnt(0)
	global_load_dwordx4 v[56:59], v48, s[12:13]
	v_subrev_u32_e32 v3, 0x5c00, v48
	v_max_i32_e32 v3, 0, v3
	global_load_dwordx4 v[72:75], v3, s[12:13]
	global_load_dwordx4 v[92:95], v24, s[20:21]
	global_load_dwordx4 v[96:99], v24, s[20:21] offset:16
	global_load_dwordx4 v[60:63], v49, s[12:13]
	v_subrev_u32_e32 v3, 0x5c00, v49
	v_max_i32_e32 v3, 0, v3
	global_load_dwordx4 v[76:79], v3, s[12:13]
	global_load_dwordx4 v[100:103], v25, s[20:21]
	global_load_dwordx4 v[104:107], v25, s[20:21] offset:16
	global_load_dwordx4 v[64:67], v50, s[12:13]
	v_subrev_u32_e32 v3, 0x5c00, v50
	v_max_i32_e32 v3, 0, v3
	global_load_dwordx4 v[80:83], v3, s[12:13]
	global_load_dwordx4 v[108:111], v26, s[20:21]
	global_load_dwordx4 v[112:115], v26, s[20:21] offset:16
	s_lshl_b32 s5, s28, 11
	s_add_u32 s5, s5, 0x7ff
	s_add_u32 s6, s28, 0x1ffc
	s_cmp_lt_u32 s28, 4
	s_cselect_b32 s5, s5, s6
	s_mul_i32 s5, s5, 0x5c00
	s_mul_i32 s6, s28, 0x3480
	s_add_u32 s7, s6, 0x4200000
	s_add_u32 s6, s6, 0x6458000
	s_cmp_lt_u32 s28, 4
	s_cselect_b32 s6, s7, s6
	s_add_u32 s24, s82, s6
	s_addc_u32 s25, s83, 0
	s_add_u32 s26, s12, s5
	s_addc_u32 s27, s13, 0
	v_lshlrev_b32_e32 v3, 4, v34
	v_lshlrev_b32_e32 v140, 5, v34
	v_cmp_gt_u32_e32 vcc, 0x1a4, v34
	s_cmp_lt_u32 s28, 0x84
	s_cselect_b64 s[30:31], -1, 0
	s_and_b64 s[30:31], s[30:31], vcc
	s_mov_b64 s[40:41], exec
	s_and_b64 exec, exec, s[30:31]
	global_load_dwordx4 v[136:139], v3, s[26:27]
	s_mov_b64 exec, s[40:41]
	s_cmp_ge_u32 s28, 24
	s_cbranch_scc1 .Llin_no3
	global_load_dwordx4 v[68:71], v51, s[12:13]
	v_min_u32_e32 v3, 0x207f, v43
	v_subrev_u32_e32 v3, 0x2000, v3
	v_mov_b32_e32 v4, 0x3480
	v_mul_lo_u32 v3, v3, v4
	v_add_u32_e32 v3, v3, v27
	global_load_dwordx4 v[84:87], v3, s[22:23]
	global_load_dwordx4 v[88:91], v3, s[22:23] offset:16
	global_load_dwordx4 v[116:119], v27, s[20:21]
	global_load_dwordx4 v[120:123], v27, s[20:21] offset:16
.Llin_no3:
	s_waitcnt vmcnt(8)
	v_lshlrev_b32_e32 v2, 16, v56
	v_and_b32_e32 v3, 0xffff0000, v56
	v_lshlrev_b32_e32 v4, 16, v57
	v_and_b32_e32 v5, 0xffff0000, v57
	v_lshlrev_b32_e32 v6, 16, v58
	v_and_b32_e32 v7, 0xffff0000, v58
	v_lshlrev_b32_e32 v8, 16, v59
	v_and_b32_e32 v9, 0xffff0000, v59
	v_and_b32_e32 v18, 0x7ff, v40
	v_cmp_eq_u32_e32 vcc, 0, v18
	v_cndmask_b32_e64 v72, v72, 0, vcc
	v_cndmask_b32_e64 v73, v73, 0, vcc
	v_cndmask_b32_e64 v74, v74, 0, vcc
	v_cndmask_b32_e64 v75, v75, 0, vcc
	v_lshlrev_b32_e32 v10, 16, v72
	v_and_b32_e32 v11, 0xffff0000, v72
	v_lshlrev_b32_e32 v12, 16, v73
	v_and_b32_e32 v13, 0xffff0000, v73
	v_lshlrev_b32_e32 v14, 16, v74
	v_and_b32_e32 v15, 0xffff0000, v74
	v_lshlrev_b32_e32 v16, 16, v75
	v_and_b32_e32 v17, 0xffff0000, v75
	v_sub_f32_e32 v10, v10, v2
	v_sub_f32_e32 v11, v11, v3
	v_sub_f32_e32 v12, v12, v4
	v_sub_f32_e32 v13, v13, v5
	v_sub_f32_e32 v14, v14, v6
	v_sub_f32_e32 v15, v15, v7
	v_sub_f32_e32 v16, v16, v8
	v_sub_f32_e32 v17, v17, v9
	v_fmac_f32_e32 v2, v92, v10
	v_fmac_f32_e32 v3, v93, v11
	v_fmac_f32_e32 v4, v94, v12
	v_fmac_f32_e32 v5, v95, v13
	v_fmac_f32_e32 v6, v96, v14
	v_fmac_f32_e32 v7, v97, v15
	v_fmac_f32_e32 v8, v98, v16
	v_fmac_f32_e32 v9, v99, v17
	v_mul_f32_e32 v10, v124, v2
	v_mul_f32_e32 v11, v124, v3
	v_mul_f32_e32 v12, v124, v4
	v_mul_f32_e32 v13, v124, v5
	v_mul_f32_e32 v14, v124, v6
	v_mul_f32_e32 v15, v124, v7
	v_mul_f32_e32 v16, v124, v8
	v_mul_f32_e32 v17, v124, v9
	v_exp_f32_e32 v10, v10
	v_exp_f32_e32 v11, v11
	v_exp_f32_e32 v12, v12
	v_exp_f32_e32 v13, v13
	v_exp_f32_e32 v14, v14
	v_exp_f32_e32 v15, v15
	v_exp_f32_e32 v16, v16
	v_exp_f32_e32 v17, v17
	v_add_f32_e32 v10, 1.0, v10
	v_add_f32_e32 v11, 1.0, v11
	v_add_f32_e32 v12, 1.0, v12
	v_add_f32_e32 v13, 1.0, v13
	v_add_f32_e32 v14, 1.0, v14
	v_add_f32_e32 v15, 1.0, v15
	v_add_f32_e32 v16, 1.0, v16
	v_add_f32_e32 v17, 1.0, v17
	v_rcp_f32_e32 v10, v10
	v_rcp_f32_e32 v11, v11
	v_rcp_f32_e32 v12, v12
	v_rcp_f32_e32 v13, v13
	v_rcp_f32_e32 v14, v14
	v_rcp_f32_e32 v15, v15
	v_rcp_f32_e32 v16, v16
	v_rcp_f32_e32 v17, v17
	v_sub_u32_e32 v18, v44, v1
	v_cmp_gt_u32_e32 vcc, 8, v18
	v_fma_f32 v10, v128, v10, v132
	v_fma_f32 v11, v128, v11, v132
	v_fma_f32 v12, v128, v12, v132
	v_fma_f32 v13, v128, v13, v132
	v_fma_f32 v14, v128, v14, v132
	v_fma_f32 v15, v128, v15, v132
	v_fma_f32 v16, v128, v16, v132
	v_fma_f32 v17, v128, v17, v132
	v_cndmask_b32_e32 v10, v10, v2, vcc
	v_cndmask_b32_e32 v11, v11, v3, vcc
	v_cndmask_b32_e32 v12, v12, v4, vcc
	v_cndmask_b32_e32 v13, v13, v5, vcc
	v_cndmask_b32_e32 v14, v14, v6, vcc
	v_cndmask_b32_e32 v15, v15, v7, vcc
	v_cndmask_b32_e32 v16, v16, v8, vcc
	v_cndmask_b32_e32 v17, v17, v9, vcc
	v_cvt_pk_bf16_f32 v20, v10, v11
	v_cvt_pk_bf16_f32 v21, v12, v13
	v_cvt_pk_bf16_f32 v22, v14, v15
	v_cvt_pk_bf16_f32 v23, v16, v17
	v_cmp_gt_u32_e32 vcc, 36, v44
	v_cmp_gt_u32_e64 s[2:3], s33, v40
	s_and_b64 vcc, vcc, s[2:3]
	v_cndmask_b32_e32 v20, 0, v20, vcc
	v_cndmask_b32_e32 v21, 0, v21, vcc
	v_cndmask_b32_e32 v22, 0, v22, vcc
	v_cndmask_b32_e32 v23, 0, v23, vcc
	global_store_dwordx4 v52, v[20:23], s[18:19] sc1
	s_waitcnt vmcnt(5)
	v_lshlrev_b32_e32 v2, 16, v60
	v_and_b32_e32 v3, 0xffff0000, v60
	v_lshlrev_b32_e32 v4, 16, v61
	v_and_b32_e32 v5, 0xffff0000, v61
	v_lshlrev_b32_e32 v6, 16, v62
	v_and_b32_e32 v7, 0xffff0000, v62
	v_lshlrev_b32_e32 v8, 16, v63
	v_and_b32_e32 v9, 0xffff0000, v63
	v_and_b32_e32 v18, 0x7ff, v41
	v_cmp_eq_u32_e32 vcc, 0, v18
	v_cndmask_b32_e64 v76, v76, 0, vcc
	v_cndmask_b32_e64 v77, v77, 0, vcc
	v_cndmask_b32_e64 v78, v78, 0, vcc
	v_cndmask_b32_e64 v79, v79, 0, vcc
	v_lshlrev_b32_e32 v10, 16, v76
	v_and_b32_e32 v11, 0xffff0000, v76
	v_lshlrev_b32_e32 v12, 16, v77
	v_and_b32_e32 v13, 0xffff0000, v77
	v_lshlrev_b32_e32 v14, 16, v78
	v_and_b32_e32 v15, 0xffff0000, v78
	v_lshlrev_b32_e32 v16, 16, v79
	v_and_b32_e32 v17, 0xffff0000, v79
	v_sub_f32_e32 v10, v10, v2
	v_sub_f32_e32 v11, v11, v3
	v_sub_f32_e32 v12, v12, v4
	v_sub_f32_e32 v13, v13, v5
	v_sub_f32_e32 v14, v14, v6
	v_sub_f32_e32 v15, v15, v7
	v_sub_f32_e32 v16, v16, v8
	v_sub_f32_e32 v17, v17, v9
	v_fmac_f32_e32 v2, v100, v10
	v_fmac_f32_e32 v3, v101, v11
	v_fmac_f32_e32 v4, v102, v12
	v_fmac_f32_e32 v5, v103, v13
	v_fmac_f32_e32 v6, v104, v14
	v_fmac_f32_e32 v7, v105, v15
	v_fmac_f32_e32 v8, v106, v16
	v_fmac_f32_e32 v9, v107, v17
	v_mul_f32_e32 v10, v125, v2
	v_mul_f32_e32 v11, v125, v3
	v_mul_f32_e32 v12, v125, v4
	v_mul_f32_e32 v13, v125, v5
	v_mul_f32_e32 v14, v125, v6
	v_mul_f32_e32 v15, v125, v7
	v_mul_f32_e32 v16, v125, v8
	v_mul_f32_e32 v17, v125, v9
	v_exp_f32_e32 v10, v10
	v_exp_f32_e32 v11, v11
	v_exp_f32_e32 v12, v12
	v_exp_f32_e32 v13, v13
	v_exp_f32_e32 v14, v14
	v_exp_f32_e32 v15, v15
	v_exp_f32_e32 v16, v16
	v_exp_f32_e32 v17, v17
	v_add_f32_e32 v10, 1.0, v10
	v_add_f32_e32 v11, 1.0, v11
	v_add_f32_e32 v12, 1.0, v12
	v_add_f32_e32 v13, 1.0, v13
	v_add_f32_e32 v14, 1.0, v14
	v_add_f32_e32 v15, 1.0, v15
	v_add_f32_e32 v16, 1.0, v16
	v_add_f32_e32 v17, 1.0, v17
	v_rcp_f32_e32 v10, v10
	v_rcp_f32_e32 v11, v11
	v_rcp_f32_e32 v12, v12
	v_rcp_f32_e32 v13, v13
	v_rcp_f32_e32 v14, v14
	v_rcp_f32_e32 v15, v15
	v_rcp_f32_e32 v16, v16
	v_rcp_f32_e32 v17, v17
	v_sub_u32_e32 v18, v45, v1
	v_cmp_gt_u32_e32 vcc, 8, v18
	v_fma_f32 v10, v129, v10, v133
	v_fma_f32 v11, v129, v11, v133
	v_fma_f32 v12, v129, v12, v133
	v_fma_f32 v13, v129, v13, v133
	v_fma_f32 v14, v129, v14, v133
	v_fma_f32 v15, v129, v15, v133
	v_fma_f32 v16, v129, v16, v133
	v_fma_f32 v17, v129, v17, v133
	v_cndmask_b32_e32 v10, v10, v2, vcc
	v_cndmask_b32_e32 v11, v11, v3, vcc
	v_cndmask_b32_e32 v12, v12, v4, vcc
	v_cndmask_b32_e32 v13, v13, v5, vcc
	v_cndmask_b32_e32 v14, v14, v6, vcc
	v_cndmask_b32_e32 v15, v15, v7, vcc
	v_cndmask_b32_e32 v16, v16, v8, vcc
	v_cndmask_b32_e32 v17, v17, v9, vcc
	v_cvt_pk_bf16_f32 v20, v10, v11
	v_cvt_pk_bf16_f32 v21, v12, v13
	v_cvt_pk_bf16_f32 v22, v14, v15
	v_cvt_pk_bf16_f32 v23, v16, v17
	v_cmp_gt_u32_e32 vcc, 36, v45
	v_cmp_gt_u32_e64 s[2:3], s33, v41
	s_and_b64 vcc, vcc, s[2:3]
	v_cndmask_b32_e32 v20, 0, v20, vcc
	v_cndmask_b32_e32 v21, 0, v21, vcc
	v_cndmask_b32_e32 v22, 0, v22, vcc
	v_cndmask_b32_e32 v23, 0, v23, vcc
	global_store_dwordx4 v53, v[20:23], s[18:19] sc1
	s_waitcnt vmcnt(2)
	v_lshlrev_b32_e32 v2, 16, v64
	v_and_b32_e32 v3, 0xffff0000, v64
	v_lshlrev_b32_e32 v4, 16, v65
	v_and_b32_e32 v5, 0xffff0000, v65
	v_lshlrev_b32_e32 v6, 16, v66
	v_and_b32_e32 v7, 0xffff0000, v66
	v_lshlrev_b32_e32 v8, 16, v67
	v_and_b32_e32 v9, 0xffff0000, v67
	v_and_b32_e32 v18, 0x7ff, v42
	v_cmp_eq_u32_e32 vcc, 0, v18
	v_cndmask_b32_e64 v80, v80, 0, vcc
	v_cndmask_b32_e64 v81, v81, 0, vcc
	v_cndmask_b32_e64 v82, v82, 0, vcc
	v_cndmask_b32_e64 v83, v83, 0, vcc
	v_lshlrev_b32_e32 v10, 16, v80
	v_and_b32_e32 v11, 0xffff0000, v80
	v_lshlrev_b32_e32 v12, 16, v81
	v_and_b32_e32 v13, 0xffff0000, v81
	v_lshlrev_b32_e32 v14, 16, v82
	v_and_b32_e32 v15, 0xffff0000, v82
	v_lshlrev_b32_e32 v16, 16, v83
	v_and_b32_e32 v17, 0xffff0000, v83
	v_sub_f32_e32 v10, v10, v2
	v_sub_f32_e32 v11, v11, v3
	v_sub_f32_e32 v12, v12, v4
	v_sub_f32_e32 v13, v13, v5
	v_sub_f32_e32 v14, v14, v6
	v_sub_f32_e32 v15, v15, v7
	v_sub_f32_e32 v16, v16, v8
	v_sub_f32_e32 v17, v17, v9
	v_fmac_f32_e32 v2, v108, v10
	v_fmac_f32_e32 v3, v109, v11
	v_fmac_f32_e32 v4, v110, v12
	v_fmac_f32_e32 v5, v111, v13
	v_fmac_f32_e32 v6, v112, v14
	v_fmac_f32_e32 v7, v113, v15
	v_fmac_f32_e32 v8, v114, v16
	v_fmac_f32_e32 v9, v115, v17
	v_mul_f32_e32 v10, v126, v2
	v_mul_f32_e32 v11, v126, v3
	v_mul_f32_e32 v12, v126, v4
	v_mul_f32_e32 v13, v126, v5
	v_mul_f32_e32 v14, v126, v6
	v_mul_f32_e32 v15, v126, v7
	v_mul_f32_e32 v16, v126, v8
	v_mul_f32_e32 v17, v126, v9
	v_exp_f32_e32 v10, v10
	v_exp_f32_e32 v11, v11
	v_exp_f32_e32 v12, v12
	v_exp_f32_e32 v13, v13
	v_exp_f32_e32 v14, v14
	v_exp_f32_e32 v15, v15
	v_exp_f32_e32 v16, v16
	v_exp_f32_e32 v17, v17
	v_add_f32_e32 v10, 1.0, v10
	v_add_f32_e32 v11, 1.0, v11
	v_add_f32_e32 v12, 1.0, v12
	v_add_f32_e32 v13, 1.0, v13
	v_add_f32_e32 v14, 1.0, v14
	v_add_f32_e32 v15, 1.0, v15
	v_add_f32_e32 v16, 1.0, v16
	v_add_f32_e32 v17, 1.0, v17
	v_rcp_f32_e32 v10, v10
	v_rcp_f32_e32 v11, v11
	v_rcp_f32_e32 v12, v12
	v_rcp_f32_e32 v13, v13
	v_rcp_f32_e32 v14, v14
	v_rcp_f32_e32 v15, v15
	v_rcp_f32_e32 v16, v16
	v_rcp_f32_e32 v17, v17
	v_sub_u32_e32 v18, v46, v1
	v_cmp_gt_u32_e32 vcc, 8, v18
	v_fma_f32 v10, v130, v10, v134
	v_fma_f32 v11, v130, v11, v134
	v_fma_f32 v12, v130, v12, v134
	v_fma_f32 v13, v130, v13, v134
	v_fma_f32 v14, v130, v14, v134
	v_fma_f32 v15, v130, v15, v134
	v_fma_f32 v16, v130, v16, v134
	v_fma_f32 v17, v130, v17, v134
	v_cndmask_b32_e32 v10, v10, v2, vcc
	v_cndmask_b32_e32 v11, v11, v3, vcc
	v_cndmask_b32_e32 v12, v12, v4, vcc
	v_cndmask_b32_e32 v13, v13, v5, vcc
	v_cndmask_b32_e32 v14, v14, v6, vcc
	v_cndmask_b32_e32 v15, v15, v7, vcc
	v_cndmask_b32_e32 v16, v16, v8, vcc
	v_cndmask_b32_e32 v17, v17, v9, vcc
	v_cvt_pk_bf16_f32 v20, v10, v11
	v_cvt_pk_bf16_f32 v21, v12, v13
	v_cvt_pk_bf16_f32 v22, v14, v15
	v_cvt_pk_bf16_f32 v23, v16, v17
	v_cmp_gt_u32_e32 vcc, 36, v46
	v_cmp_gt_u32_e64 s[2:3], s33, v42
	s_and_b64 vcc, vcc, s[2:3]
	v_cndmask_b32_e32 v20, 0, v20, vcc
	v_cndmask_b32_e32 v21, 0, v21, vcc
	v_cndmask_b32_e32 v22, 0, v22, vcc
	v_cndmask_b32_e32 v23, 0, v23, vcc
	global_store_dwordx4 v54, v[20:23], s[18:19] sc1
	s_cmp_ge_u32 s28, 24
	s_cbranch_scc1 .Llin_s3
	s_waitcnt vmcnt(3)
	v_lshlrev_b32_e32 v2, 16, v68
	v_and_b32_e32 v3, 0xffff0000, v68
	v_lshlrev_b32_e32 v4, 16, v69
	v_and_b32_e32 v5, 0xffff0000, v69
	v_lshlrev_b32_e32 v6, 16, v70
	v_and_b32_e32 v7, 0xffff0000, v70
	v_lshlrev_b32_e32 v8, 16, v71
	v_and_b32_e32 v9, 0xffff0000, v71
	v_mov_b32_e32 v10, v84
	v_mov_b32_e32 v11, v85
	v_mov_b32_e32 v12, v86
	v_mov_b32_e32 v13, v87
	v_mov_b32_e32 v14, v88
	v_mov_b32_e32 v15, v89
	v_mov_b32_e32 v16, v90
	v_mov_b32_e32 v17, v91
	v_sub_f32_e32 v10, v10, v2
	v_sub_f32_e32 v11, v11, v3
	v_sub_f32_e32 v12, v12, v4
	v_sub_f32_e32 v13, v13, v5
	v_sub_f32_e32 v14, v14, v6
	v_sub_f32_e32 v15, v15, v7
	v_sub_f32_e32 v16, v16, v8
	v_sub_f32_e32 v17, v17, v9
	v_fmac_f32_e32 v2, v116, v10
	v_fmac_f32_e32 v3, v117, v11
	v_fmac_f32_e32 v4, v118, v12
	v_fmac_f32_e32 v5, v119, v13
	v_fmac_f32_e32 v6, v120, v14
	v_fmac_f32_e32 v7, v121, v15
	v_fmac_f32_e32 v8, v122, v16
	v_fmac_f32_e32 v9, v123, v17
	v_mul_f32_e32 v10, v127, v2
	v_mul_f32_e32 v11, v127, v3
	v_mul_f32_e32 v12, v127, v4
	v_mul_f32_e32 v13, v127, v5
	v_mul_f32_e32 v14, v127, v6
	v_mul_f32_e32 v15, v127, v7
	v_mul_f32_e32 v16, v127, v8
	v_mul_f32_e32 v17, v127, v9
	v_exp_f32_e32 v10, v10
	v_exp_f32_e32 v11, v11
	v_exp_f32_e32 v12, v12
	v_exp_f32_e32 v13, v13
	v_exp_f32_e32 v14, v14
	v_exp_f32_e32 v15, v15
	v_exp_f32_e32 v16, v16
	v_exp_f32_e32 v17, v17
	v_add_f32_e32 v10, 1.0, v10
	v_add_f32_e32 v11, 1.0, v11
	v_add_f32_e32 v12, 1.0, v12
	v_add_f32_e32 v13, 1.0, v13
	v_add_f32_e32 v14, 1.0, v14
	v_add_f32_e32 v15, 1.0, v15
	v_add_f32_e32 v16, 1.0, v16
	v_add_f32_e32 v17, 1.0, v17
	v_rcp_f32_e32 v10, v10
	v_rcp_f32_e32 v11, v11
	v_rcp_f32_e32 v12, v12
	v_rcp_f32_e32 v13, v13
	v_rcp_f32_e32 v14, v14
	v_rcp_f32_e32 v15, v15
	v_rcp_f32_e32 v16, v16
	v_rcp_f32_e32 v17, v17
	v_sub_u32_e32 v18, v47, v1
	v_cmp_gt_u32_e32 vcc, 8, v18
	v_fma_f32 v10, v131, v10, v135
	v_fma_f32 v11, v131, v11, v135
	v_fma_f32 v12, v131, v12, v135
	v_fma_f32 v13, v131, v13, v135
	v_fma_f32 v14, v131, v14, v135
	v_fma_f32 v15, v131, v15, v135
	v_fma_f32 v16, v131, v16, v135
	v_fma_f32 v17, v131, v17, v135
	v_cndmask_b32_e32 v10, v10, v2, vcc
	v_cndmask_b32_e32 v11, v11, v3, vcc
	v_cndmask_b32_e32 v12, v12, v4, vcc
	v_cndmask_b32_e32 v13, v13, v5, vcc
	v_cndmask_b32_e32 v14, v14, v6, vcc
	v_cndmask_b32_e32 v15, v15, v7, vcc
	v_cndmask_b32_e32 v16, v16, v8, vcc
	v_cndmask_b32_e32 v17, v17, v9, vcc
	v_cvt_pk_bf16_f32 v20, v10, v11
	v_cvt_pk_bf16_f32 v21, v12, v13
	v_cvt_pk_bf16_f32 v22, v14, v15
	v_cvt_pk_bf16_f32 v23, v16, v17
	v_cmp_gt_u32_e32 vcc, 36, v47
	v_cmp_gt_u32_e64 s[2:3], s33, v43
	s_and_b64 vcc, vcc, s[2:3]
	v_cndmask_b32_e32 v20, 0, v20, vcc
	v_cndmask_b32_e32 v21, 0, v21, vcc
	v_cndmask_b32_e32 v22, 0, v22, vcc
	v_cndmask_b32_e32 v23, 0, v23, vcc
	global_store_dwordx4 v55, v[20:23], s[18:19] sc1
.Llin_s3:
	s_waitcnt vmcnt(0)
	s_and_b64 exec, exec, s[30:31]
	v_lshlrev_b32_e32 v2, 16, v136
	v_and_b32_e32 v3, 0xffff0000, v136
	v_lshlrev_b32_e32 v4, 16, v137
	v_and_b32_e32 v5, 0xffff0000, v137
	v_lshlrev_b32_e32 v6, 16, v138
	v_and_b32_e32 v7, 0xffff0000, v138
	v_lshlrev_b32_e32 v8, 16, v139
	v_and_b32_e32 v9, 0xffff0000, v139
	global_store_dwordx4 v140, v[2:5], s[24:25]
	global_store_dwordx4 v140, v[6:9], s[24:25] offset:16
	s_mov_b64 exec, s[40:41]
	s_mov_b64 s[16:17], exec
	s_branch .LBB0_702
.Llin_orig:
	s_add_u32 s12, s34, 0xd322200
	s_mov_b32 s29, 0
	v_mov_b32_e32 v17, 0
	s_addc_u32 s13, s35, 0
	s_lshl_b64 s[2:3], s[28:29], 9
	v_mov_b32_e32 v35, v17
	v_lshl_add_u64 v[2:3], s[2:3], 0, v[34:35]
	s_mov_b32 s14, s88
	s_mov_b32 s15, s29
	s_mov_b64 s[2:3], 0x63000
	s_lshl_b64 s[10:11], s[14:15], 9
	v_cmp_gt_u64_e32 vcc, s[2:3], v[2:3]
	s_and_saveexec_b64 s[16:17], vcc
	s_cbranch_execz .LBB0_686
	s_add_u32 s18, s34, 0x8af2200
	s_addc_u32 s19, s35, 0
	s_mov_b64 s[20:21], 0
	s_mov_b32 s2, 0xaaaaaaab
	s_mov_b64 s[22:23], 0x617ff
	s_movk_i32 s3, 0x5c00
	s_mov_b64 s[24:25], 0x5ffff
	s_movk_i32 s4, 0x3480
	s_mov_b32 s5, 0x3f200000
	s_mov_b32 s29, 0x3fb8aa3b
	s_mov_b32 s30, 0xc2ce8ed0
	s_mov_b32 s31, 0x42b17218
	v_mov_b32_e32 v1, 0x3ca908c9
	s_brev_b32 s33, -2
	s_movk_i32 s54, 0x300
	s_mov_b64 s[26:27], 0x62fff
	v_mov_b32_e32 v24, 0x7f800000
	v_mov_b64_e32 v[18:19], v[2:3]
	s_branch .LBB0_614
